# v97 + P0 xn rows: norm_w hoisted into registers (drops 16 serialized reloads + vmcnt(0) drains per row pair)
# speedup vs baseline: 1.0105x; 1.0003x over previous
; #define XN_LOAD(V, r_) do { const float* src_ = (r_) < MTOK ? a.in[0] + (size_t)(r_) * DM : a.in[1] + (size_t)((r_) - MTOK) * DM; \
;         _Pragma("unroll") for (int j = 0; j < 8; ++j) (V)[j] = __builtin_nontemporal_load((const f32x4*)(src_ + 4 * lane + 256 * j)); } while (0)
; __device__ __forceinline__ void p0_xn_rows(Frame& F, const Args& a, int wg, int nwg) {
;     bf16_t* XN = (bf16_t*)(a.ws + WS_XN);
;     const int gw = wg * NWAVES + F.wave, NGW = nwg * NWAVES, lane = F.lane;
;     const float* nw = a.in[2];
;     if (gw >= MROWS) return;
;     ...
;     f32x4 va[8], vb[8];
;     XN_LOAD(va, gw);
;     for (int r = gw; r < MROWS; r += 2 * NGW) {
;         const int r1 = r + NGW < MROWS ? r + NGW : r, r2 = r + 2 * NGW < MROWS ? r + 2 * NGW : r;
;         XN_LOAD(vb, r1); XN_DO(va, r); XN_LOAD(va, r2); XN_DO(vb, r1);
;     }
.LBB0_94:
	s_and_b64 vcc, exec, s[2:3]
	s_cbranch_vccz .LBB0_131
	s_mov_b64 s[2:3], -1
	s_and_b64 vcc, exec, s[96:97]
	s_cbranch_vccz .LBB0_100
	s_mul_i32 s0, s81, 28
	s_add_i32 s0, s94, s0
	s_lshl_b32 s0, s0, 3
	s_add_i32 s4, s0, s78
	s_cmpk_gt_i32 s4, 0x200f
	s_cbranch_scc1 .LBB0_99
	s_add_i32 s0, s4, 0xffffe000
	s_ashr_i32 s5, s4, 31
	s_cmpk_lt_i32 s4, 0x2000
	s_cselect_b32 s1, s5, 0
	s_cselect_b32 s0, s4, s0
	s_cselect_b32 s2, s37, s39
	s_cselect_b32 s3, s36, s38
	s_lshl_b64 s[0:1], s[0:1], 13
	s_add_u32 s0, s3, s0
	s_addc_u32 s1, s2, s1
	v_mov_b32_e32 v71, 0
	v_lshlrev_b32_e32 v70, 4, v254
	s_waitcnt vmcnt(6)
	v_lshl_add_u64 v[2:3], s[0:1], 0, v[70:71]
	s_add_u32 s84, s40, 0x1000
	s_addc_u32 s85, s41, 0
	global_load_dwordx4 v[216:219], v70, s[40:41]
	global_load_dwordx4 v[220:223], v70, s[40:41] offset:1024
	global_load_dwordx4 v[224:227], v70, s[40:41] offset:2048
	global_load_dwordx4 v[228:231], v70, s[40:41] offset:3072
	global_load_dwordx4 v[232:235], v70, s[84:85]
	global_load_dwordx4 v[236:239], v70, s[84:85] offset:1024
	global_load_dwordx4 v[240:243], v70, s[84:85] offset:2048
	global_load_dwordx4 v[244:247], v70, s[84:85] offset:3072
	global_load_dwordx4 v[30:33], v70, s[0:1] nt
	global_load_dwordx4 v[26:29], v70, s[0:1] offset:1024 nt
	global_load_dwordx4 v[18:21], v70, s[0:1] offset:2048 nt
	global_load_dwordx4 v[10:13], v70, s[0:1] offset:3072 nt
	s_movk_i32 s0, 0x1000
	v_add_co_u32_e32 v2, vcc, s0, v2
	v_mbcnt_lo_u32_b32 v1, -1, 0
	s_nop 0
	v_addc_co_u32_e32 v3, vcc, 0, v3, vcc
	global_load_dwordx4 v[22:25], v[2:3], off nt
	global_load_dwordx4 v[14:17], v[2:3], off offset:1024 nt
	global_load_dwordx4 v[6:9], v[2:3], off offset:2048 nt
	s_nop 0
	global_load_dwordx4 v[2:5], v[2:3], off offset:3072 nt
	v_mbcnt_hi_u32_b32 v35, -1, v1
	v_and_b32_e32 v1, 64, v35
	v_add_u32_e32 v36, 64, v1
	v_xor_b32_e32 v1, 1, v35
	v_cmp_lt_i32_e32 vcc, v1, v36
	v_xor_b32_e32 v37, 2, v35
	v_lshl_add_u64 v[74:75], s[40:41], 0, v[70:71]
	v_cndmask_b32_e32 v1, v35, v1, vcc
	v_cmp_lt_i32_e32 vcc, v37, v36
	s_mov_b64 s[6:7], 0x1000
	v_lshl_add_u64 v[76:77], v[74:75], 0, s[6:7]
	v_cndmask_b32_e32 v37, v35, v37, vcc
	v_lshlrev_b32_e32 v87, 2, v37
	v_xor_b32_e32 v37, 4, v35
	v_cmp_lt_i32_e32 vcc, v37, v36
	s_mov_b64 s[6:7], 0x1400
	v_lshl_add_u64 v[78:79], v[74:75], 0, s[6:7]
	v_cndmask_b32_e32 v37, v35, v37, vcc
	v_lshlrev_b32_e32 v96, 2, v37
	v_xor_b32_e32 v37, 8, v35
	v_cmp_lt_i32_e32 vcc, v37, v36
	s_mov_b64 s[6:7], 0x1800
	v_lshl_add_u64 v[80:81], v[74:75], 0, s[6:7]
	v_cndmask_b32_e32 v37, v35, v37, vcc
	v_lshlrev_b32_e32 v97, 2, v37
	v_xor_b32_e32 v37, 16, v35
	v_cmp_lt_i32_e32 vcc, v37, v36
	s_mov_b64 s[6:7], 0x1c00
	v_lshl_add_u64 v[82:83], v[74:75], 0, s[6:7]
	v_cndmask_b32_e32 v37, v35, v37, vcc
	v_lshlrev_b32_e32 v98, 2, v37
	v_xor_b32_e32 v37, 32, v35
	s_lshl_b64 s[6:7], s[4:5], 12
	v_cmp_lt_i32_e32 vcc, v37, v36
	s_add_u32 s6, s26, s6
	v_lshlrev_b32_e32 v36, 3, v254
	v_cndmask_b32_e32 v35, v35, v37, vcc
	v_mov_b32_e32 v37, v71
	s_addc_u32 s7, s27, s7
	v_lshlrev_b32_e32 v34, 2, v254
	v_lshl_add_u64 v[38:39], s[26:27], 0, v[36:37]
	s_mov_b64 s[2:3], 0x3a00000
	v_lshl_add_u64 v[36:37], s[6:7], 0, v[36:37]
	v_lshlrev_b32_e32 v1, 2, v1
	v_lshlrev_b32_e32 v99, 2, v35
	v_lshl_add_u64 v[72:73], v[38:39], 0, s[2:3]
	v_lshl_add_u64 v[84:85], v[36:37], 0, s[2:3]
	v_lshlrev_b32_e32 v70, 2, v34
	s_mov_b32 s6, 0x3a000000
	s_mov_b32 s1, 0x800000
	s_movk_i32 s5, 0x7fff
	s_mov_b32 s7, 0xffff0000
	s_mov_b64 s[28:29], 0xe00000
	v_mov_b32_e32 v86, 0x358637bd
.LBB0_98:
	s_add_i32 s2, s4, 0x700
	s_cmpk_lt_i32 s4, 0x1910
	s_cselect_b32 s2, s2, s4
	s_add_i32 s8, s4, 0xe00
	s_cmpk_lt_i32 s4, 0x1210
	s_cselect_b32 s9, s8, s4
	s_add_i32 s10, s2, 0xffffe000
	s_ashr_i32 s3, s2, 31
	s_waitcnt vmcnt(7)
	v_pk_mul_f32 v[42:43], v[32:33], v[32:33]
	s_waitcnt vmcnt(6)
	v_pk_mul_f32 v[44:45], v[28:29], v[28:29]
	v_pk_mul_f32 v[46:47], v[30:31], v[30:31]
	v_pk_mul_f32 v[48:49], v[26:27], v[26:27]
	s_cmpk_lt_i32 s2, 0x2000
	s_waitcnt vmcnt(5)
	v_pk_mul_f32 v[38:39], v[20:21], v[20:21]
	v_pk_mul_f32 v[40:41], v[18:19], v[18:19]
	v_mov_b32_e32 v58, v46
	v_mov_b32_e32 v59, v48
	v_mov_b32_e32 v48, v47
	v_mov_b32_e32 v46, v42
	v_mov_b32_e32 v47, v44
	v_mov_b32_e32 v44, v43
	s_cselect_b32 s11, s3, 0
	s_cselect_b32 s10, s2, s10
	v_pk_mov_b32 v[42:43], v[40:41], v[38:39] op_sel:[1,0]
	v_mov_b32_e32 v41, v39
	v_pk_add_f32 v[48:49], v[58:59], v[48:49]
	v_pk_add_f32 v[44:45], v[46:47], v[44:45]
	s_cselect_b32 s30, s37, s39
	s_cselect_b32 s31, s36, s38
	s_lshl_b64 s[10:11], s[10:11], 13
	s_waitcnt vmcnt(2)
	v_pk_mul_f32 v[34:35], v[16:17], v[16:17]
	v_pk_mul_f32 v[36:37], v[14:15], v[14:15]
	v_mul_f32_e32 v50, v10, v10
	v_mul_f32_e32 v52, v12, v12
	s_waitcnt vmcnt(1)
	v_mul_f32_e32 v54, v6, v6
	v_mul_f32_e32 v56, v8, v8
	v_pk_add_f32 v[40:41], v[42:43], v[40:41]
	v_pk_add_f32 v[42:43], v[48:49], v[44:45]
	s_add_u32 s10, s31, s10
	v_pk_fma_f32 v[38:39], v[10:11], v[10:11], v[50:51] op_sel_hi:[1,1,0]
	v_pk_fma_f32 v[50:51], v[12:13], v[12:13], v[52:53] op_sel_hi:[1,1,0]
	v_pk_mov_b32 v[52:53], v[36:37], v[34:35] op_sel:[1,0]
	v_mov_b32_e32 v37, v35
	v_pk_fma_f32 v[34:35], v[6:7], v[6:7], v[54:55] op_sel_hi:[1,1,0]
	v_pk_fma_f32 v[54:55], v[8:9], v[8:9], v[56:57] op_sel_hi:[1,1,0]
	v_pk_add_f32 v[40:41], v[40:41], v[40:41] op_sel_hi:[0,1]
	v_pk_add_f32 v[42:43], v[42:43], v[42:43] op_sel_hi:[0,1]
	s_addc_u32 s11, s30, s11
	v_mul_f32_e32 v38, v22, v22
	v_mul_f32_e32 v50, v23, v23
	s_waitcnt vmcnt(0)
; #define XN_LOAD(V, r_) do { const float* src_ = (r_) < MTOK ? a.in[0] + (size_t)(r_) * DM : a.in[1] + (size_t)((r_) - MTOK) * DM; \
;         _Pragma("unroll") for (int j = 0; j < 8; ++j) (V)[j] = __builtin_nontemporal_load((const f32x4*)(src_ + 4 * lane + 256 * j)); } while (0)
; __device__ __forceinline__ void p0_xn_rows(Frame& F, const Args& a, int wg, int nwg) {
;     ...
;     f32x4 va[8], vb[8];
;     XN_LOAD(va, gw);
;     for (int r = gw; r < MROWS; r += 2 * NGW) {
;         const int r1 = r + NGW < MROWS ? r + NGW : r, r2 = r + 2 * NGW < MROWS ? r + 2 * NGW : r;
;         XN_LOAD(vb, r1); XN_DO(va, r); XN_LOAD(va, r2); XN_DO(vb, r1);
	v_mul_f32_e32 v34, v2, v2
	v_mul_f32_e32 v54, v3, v3
	v_mul_f32_e32 v40, v24, v24
	v_mul_f32_e32 v42, v25, v25
	global_load_dwordx4 v[66:69], v70, s[10:11] nt
	global_load_dwordx4 v[58:61], v70, s[10:11] offset:1024 nt
	v_pk_add_f32 v[38:39], v[38:39], v[50:51]
	v_pk_add_f32 v[34:35], v[34:35], v[54:55]
	v_pk_add_f32 v[40:41], v[40:41], v[42:43]
	global_load_dwordx4 v[54:57], v70, s[10:11] offset:2048 nt
	v_pk_add_f32 v[36:37], v[52:53], v[36:37]
	v_pk_add_f32 v[38:39], v[38:39], v[40:41]
	v_pk_add_f32 v[36:37], v[36:37], v[36:37] op_sel_hi:[0,1]
	v_pk_add_f32 v[38:39], v[38:39], v[38:39] op_sel_hi:[0,1]
	global_load_dwordx4 v[50:53], v70, s[10:11] offset:3072 nt
	v_mul_f32_e32 v36, v4, v4
	v_mul_f32_e32 v38, v5, v5
	v_lshl_add_u64 v[40:41], s[10:11], 0, v[70:71]
	v_pk_add_f32 v[36:37], v[36:37], v[38:39]
	v_add_co_u32_e32 v38, vcc, s0, v40
	v_pk_add_f32 v[90:91], v[34:35], v[36:37]
	s_nop 0
	v_addc_co_u32_e32 v39, vcc, 0, v41, vcc
	global_load_dwordx4 v[46:49], v[38:39], off nt
	global_load_dwordx4 v[42:45], v[38:39], off offset:1024 nt
	global_load_dwordx4 v[34:37], v[38:39], off offset:3072 nt
	s_nop 0
	global_load_dwordx4 v[38:41], v[38:39], off offset:2048 nt
	v_mov_b32_e32 v93, v90
	s_add_i32 s30, s9, 0xffffe000
	s_ashr_i32 s31, s9, 31
	s_cmpk_lt_i32 s9, 0x2000
	s_cselect_b32 s11, s31, 0
	s_cselect_b32 s10, s9, s30
	s_cselect_b32 s9, s37, s39
	s_cselect_b32 s30, s36, s38
	s_lshl_b64 s[10:11], s[10:11], 13
	s_add_u32 s30, s30, s10
	s_addc_u32 s31, s9, s11
	s_lshl_b64 s[2:3], s[2:3], 12
	v_lshl_add_u64 v[94:95], s[30:31], 0, v[70:71]
	v_lshl_add_u64 v[88:89], v[72:73], 0, s[2:3]
	v_add_co_u32_e32 v94, vcc, s0, v94
	s_cmpk_gt_i32 s4, 0x120f
	s_nop 0
	v_addc_co_u32_e32 v95, vcc, 0, v95, vcc
	s_mov_b32 s4, s8
	s_waitcnt vmcnt(7)
	v_mov_b32_e32 v102, v67
	s_waitcnt vmcnt(6)
	v_mov_b32_e32 v103, v59
	v_mov_b32_e32 v106, v69
	v_mov_b32_e32 v107, v61
	v_mov_b32_e32 v100, v66
	v_mov_b32_e32 v101, v58
	v_mov_b32_e32 v104, v68
	v_mov_b32_e32 v105, v60
	s_waitcnt vmcnt(5)
	v_pk_mul_f32 v[108:109], v[56:57], v[56:57]
	v_pk_mul_f32 v[110:111], v[54:55], v[54:55]
	v_pk_mul_f32 v[102:103], v[102:103], v[102:103]
	v_pk_mul_f32 v[106:107], v[106:107], v[106:107]
	v_pk_mov_b32 v[112:113], v[110:111], v[108:109] op_sel:[1,0]
	v_mov_b32_e32 v111, v109
	v_pk_fma_f32 v[100:101], v[100:101], v[100:101], v[102:103]
	v_pk_fma_f32 v[102:103], v[104:105], v[104:105], v[106:107]
	s_waitcnt vmcnt(4)
	v_mul_f32_e32 v90, v51, v51
	v_mul_f32_e32 v92, v53, v53
	v_pk_add_f32 v[104:105], v[112:113], v[110:111]
	v_pk_add_f32 v[100:101], v[100:101], v[102:103]
	v_pk_fma_f32 v[108:109], v[50:51], v[50:51], v[90:91] op_sel_hi:[1,1,0]
	v_pk_fma_f32 v[114:115], v[52:53], v[52:53], v[92:93] op_sel_hi:[1,1,0]
	s_waitcnt vmcnt(3)
	v_mul_f32_e32 v116, v46, v46
	v_mul_f32_e32 v117, v47, v47
	v_pk_add_f32 v[102:103], v[104:105], v[104:105] op_sel:[0,1] op_sel_hi:[1,0]
	v_pk_add_f32 v[100:101], v[100:101], v[100:101] op_sel:[0,1] op_sel_hi:[1,0]
	v_mul_f32_e32 v109, v48, v48
	v_mul_f32_e32 v115, v49, v49
	s_waitcnt vmcnt(2)
	v_pk_mul_f32 v[106:107], v[44:45], v[44:45]
	v_pk_mul_f32 v[110:111], v[42:43], v[42:43]
	v_mov_b32_e32 v103, v117
	v_mov_b32_e32 v101, v116
	v_pk_mov_b32 v[104:105], v[110:111], v[106:107] op_sel:[1,0]
	v_mov_b32_e32 v111, v107
	v_pk_add_f32 v[108:109], v[108:109], v[114:115]
	v_pk_add_f32 v[100:101], v[100:101], v[102:103]
	s_waitcnt vmcnt(0)
	v_mul_f32_e32 v90, v39, v39
	v_mul_f32_e32 v92, v41, v41
	v_pk_add_f32 v[104:105], v[104:105], v[110:111]
	v_pk_add_f32 v[100:101], v[100:101], v[108:109]
	v_mul_f32_e32 v118, v34, v34
	v_mul_f32_e32 v119, v35, v35
	v_mul_f32_e32 v120, v36, v36
	v_mul_f32_e32 v121, v37, v37
	v_pk_fma_f32 v[106:107], v[38:39], v[38:39], v[90:91] op_sel_hi:[1,1,0]
	v_pk_fma_f32 v[112:113], v[40:41], v[40:41], v[92:93] op_sel_hi:[1,1,0]
	v_pk_add_f32 v[104:105], v[104:105], v[104:105] op_sel:[0,1] op_sel_hi:[1,0]
	v_pk_add_f32 v[100:101], v[100:101], v[100:101] op_sel:[0,1] op_sel_hi:[1,0]
	v_mov_b32_e32 v107, v120
	v_mov_b32_e32 v113, v121
	v_mov_b32_e32 v105, v119
	v_mov_b32_e32 v101, v118
	v_pk_add_f32 v[106:107], v[106:107], v[112:113]
	v_pk_add_f32 v[100:101], v[100:101], v[104:105]
	s_nop 0
	v_pk_add_f32 v[100:101], v[100:101], v[106:107]
	s_nop 0
	v_mov_b32_e32 v92, v100
	v_mov_b32_e32 v90, v101
	v_pk_add_f32 v[90:91], v[92:93], v[90:91]
	ds_bpermute_b32 v93, v1, v91
	ds_bpermute_b32 v92, v1, v90
	s_waitcnt lgkmcnt(0)
	v_pk_add_f32 v[90:91], v[90:91], v[92:93]
	ds_bpermute_b32 v93, v87, v91
	ds_bpermute_b32 v92, v87, v90
	s_waitcnt lgkmcnt(0)
	v_pk_add_f32 v[90:91], v[90:91], v[92:93]
	ds_bpermute_b32 v93, v96, v91
	ds_bpermute_b32 v92, v96, v90
	s_waitcnt lgkmcnt(0)
	v_pk_add_f32 v[90:91], v[90:91], v[92:93]
	ds_bpermute_b32 v93, v97, v91
	ds_bpermute_b32 v92, v97, v90
	s_waitcnt lgkmcnt(0)
	v_pk_add_f32 v[90:91], v[90:91], v[92:93]
	ds_bpermute_b32 v93, v98, v91
	ds_bpermute_b32 v92, v98, v90
	s_waitcnt lgkmcnt(0)
	v_pk_add_f32 v[90:91], v[90:91], v[92:93]
	ds_bpermute_b32 v93, v99, v91
	ds_bpermute_b32 v92, v99, v90
	s_waitcnt lgkmcnt(0)
	v_pk_add_f32 v[90:91], v[90:91], v[92:93]
	s_nop 0
	v_pk_fma_f32 v[90:91], v[90:91], s[6:7], v[86:87] op_sel_hi:[1,0,0]
	s_nop 0
	v_mul_f32_e32 v92, 0x4b800000, v91
	v_cmp_gt_f32_e64 s[2:3], s1, v91
	v_mul_f32_e32 v93, 0x4b800000, v90
	v_cmp_gt_f32_e32 vcc, s1, v90
	v_cndmask_b32_e64 v91, v91, v92, s[2:3]
	v_rsq_f32_e32 v91, v91
	v_cndmask_b32_e32 v90, v90, v93, vcc
	v_rsq_f32_e32 v90, v90
	v_mul_f32_e32 v92, 0x45800000, v91
	v_cndmask_b32_e64 v91, v91, v92, s[2:3]
	v_mul_f32_e32 v30, v30, v91
	v_mul_f32_e32 v32, v32, v91
	v_mul_f32_e32 v93, 0x45800000, v90
	v_mul_f32_e32 v31, v31, v91
	v_mul_f32_e32 v33, v33, v91
	v_mul_f32_e32 v92, v2, v91
	v_mul_f32_e32 v100, v4, v91
	v_mul_f32_e32 v2, v216, v30
	v_mul_f32_e32 v4, v218, v32
	v_cndmask_b32_e32 v90, v90, v93, vcc
	v_mul_f32_e32 v26, v26, v91
	v_mul_f32_e32 v27, v27, v91
	v_mul_f32_e32 v28, v28, v91
	v_mul_f32_e32 v29, v29, v91
	v_mul_f32_e32 v18, v18, v91
	v_mul_f32_e32 v19, v19, v91
	v_mul_f32_e32 v20, v20, v91
	v_mul_f32_e32 v21, v21, v91
	v_mul_f32_e32 v10, v10, v91
	v_mul_f32_e32 v11, v11, v91
	v_mul_f32_e32 v12, v12, v91
	v_mul_f32_e32 v13, v13, v91
	v_mul_f32_e32 v22, v22, v91
	v_mul_f32_e32 v23, v23, v91
	v_mul_f32_e32 v24, v24, v91
	v_mul_f32_e32 v25, v25, v91
	v_mul_f32_e32 v14, v14, v91
	v_mul_f32_e32 v15, v15, v91
	v_mul_f32_e32 v16, v16, v91
	v_mul_f32_e32 v17, v17, v91
	v_mul_f32_e32 v6, v6, v91
	v_mul_f32_e32 v7, v7, v91
	v_mul_f32_e32 v8, v8, v91
	v_mul_f32_e32 v9, v9, v91
	v_mul_f32_e32 v93, v3, v91
	v_mul_f32_e32 v91, v5, v91
	v_mul_f32_e32 v3, v217, v31
	v_mul_f32_e32 v5, v219, v33
	v_bfe_u32 v30, v2, 16, 1
	v_bfe_u32 v32, v4, 16, 1
	v_bfe_u32 v31, v3, 16, 1
	v_bfe_u32 v33, v5, 16, 1
	v_add3_u32 v2, v2, v30, s5
	v_add3_u32 v4, v4, v32, s5
	v_add3_u32 v3, v3, v31, s5
	v_add3_u32 v5, v5, v33, s5
	v_lshrrev_b32_e32 v2, 16, v2
	v_lshrrev_b32_e32 v4, 16, v4
	v_and_or_b32 v2, v3, s7, v2
	v_and_or_b32 v3, v5, s7, v4
	global_store_dwordx2 v[84:85], v[2:3], off
	v_mul_f32_e32 v66, v66, v90
	v_mul_f32_e32 v68, v68, v90
	v_mul_f32_e32 v67, v67, v90
	v_mul_f32_e32 v69, v69, v90
	v_mul_f32_e32 v101, v58, v90
	v_mul_f32_e32 v102, v59, v90
	v_mul_f32_e32 v54, v54, v90
	v_mul_f32_e32 v56, v56, v90
	v_mul_f32_e32 v55, v55, v90
	v_mul_f32_e32 v57, v57, v90
	v_mul_f32_e32 v50, v50, v90
	v_mul_f32_e32 v52, v52, v90
	v_mul_f32_e32 v51, v51, v90
	v_mul_f32_e32 v53, v53, v90
	v_mul_f32_e32 v46, v46, v90
	v_mul_f32_e32 v48, v48, v90
	v_mul_f32_e32 v47, v47, v90
	v_mul_f32_e32 v49, v49, v90
	v_mul_f32_e32 v42, v42, v90
	v_mul_f32_e32 v44, v44, v90
	v_mul_f32_e32 v43, v43, v90
	v_mul_f32_e32 v45, v45, v90
	v_mul_f32_e32 v38, v38, v90
	v_mul_f32_e32 v40, v40, v90
	v_mul_f32_e32 v39, v39, v90
	v_mul_f32_e32 v41, v41, v90
	v_mul_f32_e32 v34, v34, v90
	v_mul_f32_e32 v36, v36, v90
	v_mul_f32_e32 v35, v35, v90
	v_mul_f32_e32 v37, v37, v90
	v_mul_f32_e32 v2, v220, v26
	v_mul_f32_e32 v4, v222, v28
	v_mul_f32_e32 v3, v221, v27
	v_mul_f32_e32 v5, v223, v29
	v_bfe_u32 v26, v2, 16, 1
	v_bfe_u32 v28, v4, 16, 1
	v_bfe_u32 v27, v3, 16, 1
	v_bfe_u32 v29, v5, 16, 1
	v_add3_u32 v2, v2, v26, s5
	v_add3_u32 v4, v4, v28, s5
	v_add3_u32 v3, v3, v27, s5
	v_add3_u32 v5, v5, v29, s5
	v_lshrrev_b32_e32 v2, 16, v2
	v_lshrrev_b32_e32 v4, 16, v4
	v_and_or_b32 v2, v3, s7, v2
	v_and_or_b32 v3, v5, s7, v4
	global_store_dwordx2 v[84:85], v[2:3], off offset:512
	v_mul_f32_e32 v2, v224, v18
	v_mul_f32_e32 v4, v226, v20
	v_mul_f32_e32 v3, v225, v19
	v_mul_f32_e32 v5, v227, v21
	v_bfe_u32 v18, v2, 16, 1
	v_bfe_u32 v20, v4, 16, 1
	v_bfe_u32 v19, v3, 16, 1
	v_bfe_u32 v21, v5, 16, 1
	v_add3_u32 v2, v2, v18, s5
	v_add3_u32 v4, v4, v20, s5
	v_add3_u32 v3, v3, v19, s5
	v_add3_u32 v5, v5, v21, s5
	v_lshrrev_b32_e32 v2, 16, v2
	v_lshrrev_b32_e32 v4, 16, v4
	v_and_or_b32 v2, v3, s7, v2
	v_and_or_b32 v3, v5, s7, v4
	global_store_dwordx2 v[84:85], v[2:3], off offset:1024
	v_mul_f32_e32 v2, v228, v10
	v_mul_f32_e32 v4, v230, v12
	v_mul_f32_e32 v3, v229, v11
	v_mul_f32_e32 v5, v231, v13
	v_bfe_u32 v10, v2, 16, 1
	v_bfe_u32 v12, v4, 16, 1
	v_bfe_u32 v11, v3, 16, 1
	v_bfe_u32 v13, v5, 16, 1
	v_add3_u32 v2, v2, v10, s5
	v_add3_u32 v4, v4, v12, s5
	v_add3_u32 v3, v3, v11, s5
	v_add3_u32 v5, v5, v13, s5
	v_lshrrev_b32_e32 v2, 16, v2
	v_lshrrev_b32_e32 v4, 16, v4
	v_and_or_b32 v2, v3, s7, v2
	v_and_or_b32 v3, v5, s7, v4
	global_store_dwordx2 v[84:85], v[2:3], off offset:1536
	v_mul_f32_e32 v2, v232, v22
	v_mul_f32_e32 v4, v234, v24
	v_mul_f32_e32 v3, v233, v23
	v_mul_f32_e32 v5, v235, v25
	v_bfe_u32 v10, v2, 16, 1
	v_bfe_u32 v12, v4, 16, 1
	v_bfe_u32 v11, v3, 16, 1
	v_bfe_u32 v13, v5, 16, 1
	v_add3_u32 v2, v2, v10, s5
	v_add3_u32 v4, v4, v12, s5
	v_add3_u32 v3, v3, v11, s5
	v_add3_u32 v5, v5, v13, s5
	v_lshrrev_b32_e32 v2, 16, v2
	v_lshrrev_b32_e32 v4, 16, v4
	v_and_or_b32 v2, v3, s7, v2
	v_and_or_b32 v3, v5, s7, v4
	global_store_dwordx2 v[84:85], v[2:3], off offset:2048
	v_mul_f32_e32 v2, v14, v236
	v_mul_f32_e32 v4, v16, v238
	v_mul_f32_e32 v3, v15, v237
	v_mul_f32_e32 v5, v17, v239
	v_bfe_u32 v10, v2, 16, 1
	v_bfe_u32 v12, v4, 16, 1
	v_bfe_u32 v11, v3, 16, 1
	v_bfe_u32 v13, v5, 16, 1
	v_add3_u32 v2, v2, v10, s5
	v_add3_u32 v4, v4, v12, s5
	v_add3_u32 v3, v3, v11, s5
	v_add3_u32 v5, v5, v13, s5
	v_lshrrev_b32_e32 v2, 16, v2
	v_lshrrev_b32_e32 v4, 16, v4
	v_and_or_b32 v2, v3, s7, v2
	v_and_or_b32 v3, v5, s7, v4
	global_store_dwordx2 v[84:85], v[2:3], off offset:2560
	v_mul_f32_e32 v2, v6, v240
	v_mul_f32_e32 v4, v8, v242
	v_mul_f32_e32 v3, v7, v241
	v_mul_f32_e32 v5, v9, v243
	v_bfe_u32 v6, v2, 16, 1
	v_bfe_u32 v8, v4, 16, 1
	v_bfe_u32 v7, v3, 16, 1
	v_bfe_u32 v9, v5, 16, 1
	v_add3_u32 v2, v2, v6, s5
; #define XN_LOAD(V, r_) do { const float* src_ = (r_) < MTOK ? a.in[0] + (size_t)(r_) * DM : a.in[1] + (size_t)((r_) - MTOK) * DM; \
;         _Pragma("unroll") for (int j = 0; j < 8; ++j) (V)[j] = __builtin_nontemporal_load((const f32x4*)(src_ + 4 * lane + 256 * j)); } while (0)
; __device__ __forceinline__ void p0_xn_rows(Frame& F, const Args& a, int wg, int nwg) {
;     ...
;     f32x4 va[8], vb[8];
;     XN_LOAD(va, gw);
;     for (int r = gw; r < MROWS; r += 2 * NGW) {
;         const int r1 = r + NGW < MROWS ? r + NGW : r, r2 = r + 2 * NGW < MROWS ? r + 2 * NGW : r;
;         XN_LOAD(vb, r1); XN_DO(va, r); XN_LOAD(va, r2); XN_DO(vb, r1);
	v_add3_u32 v4, v4, v8, s5
	v_add3_u32 v3, v3, v7, s5
	v_add3_u32 v5, v5, v9, s5
	v_lshrrev_b32_e32 v2, 16, v2
	v_lshrrev_b32_e32 v4, 16, v4
	v_and_or_b32 v2, v3, s7, v2
	v_and_or_b32 v3, v5, s7, v4
	global_store_dwordx2 v[84:85], v[2:3], off offset:3072
	v_mul_f32_e32 v2, v92, v244
	v_mul_f32_e32 v4, v100, v246
	v_mul_f32_e32 v3, v93, v245
	v_mul_f32_e32 v5, v91, v247
	v_bfe_u32 v6, v2, 16, 1
	v_bfe_u32 v8, v4, 16, 1
	v_bfe_u32 v7, v3, 16, 1
	v_bfe_u32 v9, v5, 16, 1
	v_add3_u32 v2, v2, v6, s5
	v_add3_u32 v4, v4, v8, s5
	v_add3_u32 v3, v3, v7, s5
	v_add3_u32 v5, v5, v9, s5
	v_lshrrev_b32_e32 v2, 16, v2
	v_lshrrev_b32_e32 v4, 16, v4
	v_and_or_b32 v2, v3, s7, v2
	v_and_or_b32 v3, v5, s7, v4
	global_store_dwordx2 v[84:85], v[2:3], off offset:3584
	global_load_dwordx4 v[30:33], v70, s[30:31] nt
	global_load_dwordx4 v[26:29], v70, s[30:31] offset:1024 nt
	global_load_dwordx4 v[18:21], v70, s[30:31] offset:2048 nt
	global_load_dwordx4 v[10:13], v70, s[30:31] offset:3072 nt
	global_load_dwordx4 v[22:25], v[94:95], off nt
	global_load_dwordx4 v[14:17], v[94:95], off offset:1024 nt
	global_load_dwordx4 v[6:9], v[94:95], off offset:2048 nt
	global_load_dwordx4 v[2:5], v[94:95], off offset:3072 nt
	v_lshl_add_u64 v[84:85], v[84:85], 0, s[28:29]
	v_mul_f32_e32 v58, v216, v66
	v_mul_f32_e32 v62, v218, v68
	v_mul_f32_e32 v59, v217, v67
	v_mul_f32_e32 v63, v219, v69
	v_bfe_u32 v64, v58, 16, 1
	v_bfe_u32 v66, v62, 16, 1
	v_bfe_u32 v65, v59, 16, 1
	v_bfe_u32 v67, v63, 16, 1
	v_add3_u32 v58, v58, v64, s5
	v_add3_u32 v62, v62, v66, s5
	v_add3_u32 v59, v59, v65, s5
	v_add3_u32 v63, v63, v67, s5
	v_lshrrev_b32_e32 v58, 16, v58
	v_lshrrev_b32_e32 v62, 16, v62
	v_and_or_b32 v58, v59, s7, v58
	v_and_or_b32 v59, v63, s7, v62
	global_store_dwordx2 v[88:89], v[58:59], off
	v_mul_f32_e32 v58, v60, v90
	v_mul_f32_e32 v59, v61, v90
	v_mul_f32_e32 v60, v220, v101
	v_mul_f32_e32 v58, v222, v58
	v_mul_f32_e32 v61, v221, v102
	v_mul_f32_e32 v59, v223, v59
	v_bfe_u32 v62, v60, 16, 1
	v_bfe_u32 v64, v58, 16, 1
	v_bfe_u32 v63, v61, 16, 1
	v_bfe_u32 v65, v59, 16, 1
	v_add3_u32 v60, v60, v62, s5
	v_add3_u32 v58, v58, v64, s5
	v_add3_u32 v61, v61, v63, s5
	v_add3_u32 v59, v59, v65, s5
	v_lshrrev_b32_e32 v60, 16, v60
	v_lshrrev_b32_e32 v62, 16, v58
	v_and_or_b32 v58, v61, s7, v60
	v_and_or_b32 v59, v59, s7, v62
	global_store_dwordx2 v[88:89], v[58:59], off offset:512
	v_mul_f32_e32 v54, v224, v54
	v_mul_f32_e32 v56, v226, v56
	v_mul_f32_e32 v55, v225, v55
	v_mul_f32_e32 v57, v227, v57
	v_bfe_u32 v58, v54, 16, 1
	v_bfe_u32 v60, v56, 16, 1
	v_bfe_u32 v59, v55, 16, 1
	v_bfe_u32 v61, v57, 16, 1
	v_add3_u32 v54, v54, v58, s5
	v_add3_u32 v56, v56, v60, s5
	v_add3_u32 v55, v55, v59, s5
	v_add3_u32 v57, v57, v61, s5
	v_lshrrev_b32_e32 v54, 16, v54
	v_lshrrev_b32_e32 v56, 16, v56
	v_and_or_b32 v54, v55, s7, v54
	v_and_or_b32 v55, v57, s7, v56
	global_store_dwordx2 v[88:89], v[54:55], off offset:1024
	v_mul_f32_e32 v50, v228, v50
	v_mul_f32_e32 v52, v230, v52
	v_mul_f32_e32 v51, v229, v51
	v_mul_f32_e32 v53, v231, v53
	v_bfe_u32 v54, v50, 16, 1
	v_bfe_u32 v56, v52, 16, 1
	v_bfe_u32 v55, v51, 16, 1
	v_bfe_u32 v57, v53, 16, 1
	v_add3_u32 v50, v50, v54, s5
	v_add3_u32 v52, v52, v56, s5
	v_add3_u32 v51, v51, v55, s5
	v_add3_u32 v53, v53, v57, s5
	v_lshrrev_b32_e32 v50, 16, v50
	v_lshrrev_b32_e32 v52, 16, v52
	v_and_or_b32 v50, v51, s7, v50
	v_and_or_b32 v51, v53, s7, v52
	global_store_dwordx2 v[88:89], v[50:51], off offset:1536
	v_mul_f32_e32 v46, v232, v46
	v_mul_f32_e32 v48, v234, v48
	v_mul_f32_e32 v47, v233, v47
	v_mul_f32_e32 v49, v235, v49
	v_bfe_u32 v50, v46, 16, 1
	v_bfe_u32 v52, v48, 16, 1
	v_bfe_u32 v51, v47, 16, 1
	v_bfe_u32 v53, v49, 16, 1
	v_add3_u32 v46, v46, v50, s5
	v_add3_u32 v48, v48, v52, s5
	v_add3_u32 v47, v47, v51, s5
	v_add3_u32 v49, v49, v53, s5
	v_lshrrev_b32_e32 v46, 16, v46
	v_lshrrev_b32_e32 v48, 16, v48
	v_and_or_b32 v46, v47, s7, v46
	v_and_or_b32 v47, v49, s7, v48
	global_store_dwordx2 v[88:89], v[46:47], off offset:2048
	v_mul_f32_e32 v42, v42, v236
	v_mul_f32_e32 v44, v44, v238
	v_mul_f32_e32 v43, v43, v237
	v_mul_f32_e32 v45, v45, v239
	v_bfe_u32 v46, v42, 16, 1
	v_bfe_u32 v48, v44, 16, 1
	v_bfe_u32 v47, v43, 16, 1
	v_bfe_u32 v49, v45, 16, 1
	v_add3_u32 v42, v42, v46, s5
	v_add3_u32 v44, v44, v48, s5
	v_add3_u32 v43, v43, v47, s5
	v_add3_u32 v45, v45, v49, s5
	v_lshrrev_b32_e32 v42, 16, v42
	v_lshrrev_b32_e32 v44, 16, v44
	v_and_or_b32 v42, v43, s7, v42
	v_and_or_b32 v43, v45, s7, v44
	global_store_dwordx2 v[88:89], v[42:43], off offset:2560
	v_mul_f32_e32 v38, v38, v240
	v_mul_f32_e32 v40, v40, v242
	v_mul_f32_e32 v39, v39, v241
	v_mul_f32_e32 v41, v41, v243
	v_bfe_u32 v42, v38, 16, 1
	v_bfe_u32 v44, v40, 16, 1
	v_bfe_u32 v43, v39, 16, 1
	v_bfe_u32 v45, v41, 16, 1
	v_add3_u32 v38, v38, v42, s5
	v_add3_u32 v40, v40, v44, s5
	v_add3_u32 v39, v39, v43, s5
	v_add3_u32 v41, v41, v45, s5
	v_lshrrev_b32_e32 v38, 16, v38
	v_lshrrev_b32_e32 v40, 16, v40
	v_and_or_b32 v38, v39, s7, v38
	v_and_or_b32 v39, v41, s7, v40
	global_store_dwordx2 v[88:89], v[38:39], off offset:3072
	v_mul_f32_e32 v34, v34, v244
	v_mul_f32_e32 v36, v36, v246
	v_mul_f32_e32 v35, v35, v245
	v_mul_f32_e32 v37, v37, v247
	v_bfe_u32 v38, v34, 16, 1
	v_bfe_u32 v40, v36, 16, 1
	v_bfe_u32 v39, v35, 16, 1
	v_bfe_u32 v41, v37, 16, 1
	v_add3_u32 v34, v34, v38, s5
	v_add3_u32 v36, v36, v40, s5
	v_add3_u32 v35, v35, v39, s5
	v_add3_u32 v37, v37, v41, s5
	v_lshrrev_b32_e32 v34, 16, v34
	v_lshrrev_b32_e32 v36, 16, v36
	v_and_or_b32 v34, v35, s7, v34
	v_and_or_b32 v35, v37, s7, v36
	global_store_dwordx2 v[88:89], v[34:35], off offset:3584
	s_cbranch_scc0 .LBB0_98
